# v15 with the prompt fast tile block using plain f32 VALU instead of packed f32 ops (subtract/sum)
# speedup vs baseline: 1.0082x; 1.0082x over previous
; #define LAS __attribute__((address_space(3)))
; __device__ __forceinline__ float fexp2(float x) { return __builtin_amdgcn_exp2f(x); }
; __device__ __forceinline__ s16x4 vtr(const LAS unsigned char* p) { return __builtin_bit_cast(s16x4, __builtin_amdgcn_ds_read_tr16_b64_v4i16((LAS v4i16_t*)p)); }
; __device__ __forceinline__ bf16x8 cat8(s16x4 lo, s16x4 hi) { return (bf16x8){lo[0], lo[1], lo[2], lo[3], hi[0], hi[1], hi[2], hi[3]}; }
; template <int NEB>
; __device__ __forceinline__ void softmax_tile(f32x16& X0, f32x16& X1, float& m, float& l, f32x16 (&OT)[NEB]) {
;     ...
;     float s = 0.f;
; #pragma unroll
;     for (int r = 0; r < 16; ++r) { X0[r] = fexp2(X0[r] - m); X1[r] = fexp2(X1[r] - m); s += X0[r] + X1[r]; }
;     l += s;
; }
; template <int VRS, int NEB, bool SB = false>
; __device__ __forceinline__ void pv_tile(f32x16 (&OT)[NEB], const f32x16& X0, const f32x16& X1, const LAS unsigned char* vlane  ) {
; #pragma unroll
;     for (int kk = 0; kk < 4; ++kk) {
;         const bf16x8 pa = packp(kk < 2 ? X0 : X1, (kk & 1) * 8);
; #pragma unroll
;         for (int eb = 0; eb < NEB; ++eb) {
;             const s16x4 lo = vtr(vlane + (kk * 16) * VRS + eb * 64), hi = vtr(vlane + (kk * 16 + 8) * VRS + eb * 64);
;             OT[eb] = __builtin_amdgcn_mfma_f32_32x32x16_bf16(cat8(lo, hi), pa, OT[eb], 0, 0, 0);
;         }
;         if (SB) __builtin_amdgcn_sched_barrier(0);
;     }
; }
.Lpf0_nores:
	v_sub_f32_e32 v151, v163, v175
	v_sub_f32_e32 v66, v66, v151
	v_sub_f32_e32 v67, v67, v151
	v_sub_f32_e32 v68, v68, v151
	v_sub_f32_e32 v69, v69, v151
	v_sub_f32_e32 v70, v70, v151
	v_sub_f32_e32 v71, v71, v151
	v_sub_f32_e32 v72, v72, v151
	v_sub_f32_e32 v73, v73, v151
	v_sub_f32_e32 v74, v74, v151
	v_sub_f32_e32 v75, v75, v151
	v_sub_f32_e32 v76, v76, v151
	v_sub_f32_e32 v77, v77, v151
	v_sub_f32_e32 v78, v78, v151
	v_sub_f32_e32 v79, v79, v151
	v_sub_f32_e32 v80, v80, v151
	v_sub_f32_e32 v81, v81, v151
	v_exp_f32_e32 v66, v66
	v_exp_f32_e32 v67, v67
	v_exp_f32_e32 v68, v68
	v_exp_f32_e32 v69, v69
	v_exp_f32_e32 v70, v70
	v_exp_f32_e32 v71, v71
	v_exp_f32_e32 v72, v72
	v_exp_f32_e32 v73, v73
	v_exp_f32_e32 v74, v74
	v_exp_f32_e32 v75, v75
	v_exp_f32_e32 v76, v76
	v_exp_f32_e32 v77, v77
	v_exp_f32_e32 v78, v78
	v_exp_f32_e32 v79, v79
	v_exp_f32_e32 v80, v80
	v_exp_f32_e32 v81, v81
	v_add_f32_e32 v188, v66, v67
	v_add_f32_e32 v189, v68, v69
	v_add_f32_e32 v190, v70, v71
	v_add_f32_e32 v191, v72, v73
	v_add_f32_e32 v188, v188, v74
	v_add_f32_e32 v189, v189, v75
	v_add_f32_e32 v190, v190, v76
	v_add_f32_e32 v191, v191, v77
	v_add_f32_e32 v188, v188, v78
	v_add_f32_e32 v189, v189, v79
	v_add_f32_e32 v190, v190, v80
	v_add_f32_e32 v191, v191, v81
	v_cvt_pk_bf16_f32 v66, v66, v67
	v_cvt_pk_bf16_f32 v67, v68, v69
	v_cvt_pk_bf16_f32 v68, v70, v71
	v_cvt_pk_bf16_f32 v69, v72, v73
	v_cvt_pk_bf16_f32 v70, v74, v75
	v_cvt_pk_bf16_f32 v71, v76, v77
	v_cvt_pk_bf16_f32 v72, v78, v79
	v_cvt_pk_bf16_f32 v73, v80, v81
	ds_read_b64_tr_b16 v[74:75], v156 offset:23552
	ds_read_b64_tr_b16 v[76:77], v156 offset:26112
	ds_read_b64_tr_b16 v[78:79], v156 offset:23616
	ds_read_b64_tr_b16 v[80:81], v156 offset:26176
	ds_read_b64_tr_b16 v[244:245], v156 offset:23680
	ds_read_b64_tr_b16 v[246:247], v156 offset:26240
	ds_read_b64_tr_b16 v[248:249], v156 offset:23744
	ds_read_b64_tr_b16 v[250:251], v156 offset:26304
	s_waitcnt lgkmcnt(8)
	v_mfma_f32_32x32x16_bf16 v[50:65], v[166:169], v[66:69], v[50:65]
	v_mfma_f32_32x32x16_bf16 v[34:49], v[176:179], v[66:69], v[34:49]
	v_mfma_f32_32x32x16_bf16 v[18:33], v[180:183], v[66:69], v[18:33]
	v_mfma_f32_32x32x16_bf16 v[2:17], v[184:187], v[66:69], v[2:17]
	ds_read_b64_tr_b16 v[166:167], v156 offset:28672
	ds_read_b64_tr_b16 v[168:169], v156 offset:31232
	ds_read_b64_tr_b16 v[176:177], v156 offset:28736
	ds_read_b64_tr_b16 v[178:179], v156 offset:31296
	ds_read_b64_tr_b16 v[180:181], v156 offset:28800
	ds_read_b64_tr_b16 v[182:183], v156 offset:31360
	ds_read_b64_tr_b16 v[184:185], v156 offset:28864
	ds_read_b64_tr_b16 v[186:187], v156 offset:31424
	s_waitcnt lgkmcnt(8)
	v_mfma_f32_32x32x16_bf16 v[50:65], v[74:77], v[70:73], v[50:65]
	v_mfma_f32_32x32x16_bf16 v[34:49], v[78:81], v[70:73], v[34:49]
	v_mfma_f32_32x32x16_bf16 v[18:33], v[244:247], v[70:73], v[18:33]
	v_mfma_f32_32x32x16_bf16 v[2:17], v[248:251], v[70:73], v[2:17]
	ds_read_b64_tr_b16 v[74:75], v156 offset:33792
	ds_read_b64_tr_b16 v[76:77], v156 offset:36352
	ds_read_b64_tr_b16 v[78:79], v156 offset:33856
	ds_read_b64_tr_b16 v[80:81], v156 offset:36416
	ds_read_b64_tr_b16 v[244:245], v156 offset:33920
	ds_read_b64_tr_b16 v[246:247], v156 offset:36480
	ds_read_b64_tr_b16 v[248:249], v156 offset:33984
	ds_read_b64_tr_b16 v[250:251], v156 offset:36544
	v_sub_f32_e32 v82, v82, v151
	v_sub_f32_e32 v83, v83, v151
	v_sub_f32_e32 v84, v84, v151
	v_sub_f32_e32 v85, v85, v151
	v_sub_f32_e32 v86, v86, v151
	v_sub_f32_e32 v87, v87, v151
	v_sub_f32_e32 v88, v88, v151
	v_sub_f32_e32 v89, v89, v151
	v_sub_f32_e32 v90, v90, v151
	v_sub_f32_e32 v91, v91, v151
	v_sub_f32_e32 v92, v92, v151
	v_sub_f32_e32 v93, v93, v151
	v_sub_f32_e32 v94, v94, v151
	v_sub_f32_e32 v95, v95, v151
	v_sub_f32_e32 v96, v96, v151
	v_sub_f32_e32 v97, v97, v151
	v_exp_f32_e32 v82, v82
	v_exp_f32_e32 v83, v83
	v_exp_f32_e32 v84, v84
	v_exp_f32_e32 v85, v85
	v_exp_f32_e32 v86, v86
	v_exp_f32_e32 v87, v87
	v_exp_f32_e32 v88, v88
	v_exp_f32_e32 v89, v89
	v_exp_f32_e32 v90, v90
	v_exp_f32_e32 v91, v91
	v_exp_f32_e32 v92, v92
	v_exp_f32_e32 v93, v93
	v_exp_f32_e32 v94, v94
	v_exp_f32_e32 v95, v95
	v_exp_f32_e32 v96, v96
	v_exp_f32_e32 v97, v97
	v_add_f32_e32 v188, v188, v82
	v_add_f32_e32 v189, v189, v83
	v_add_f32_e32 v190, v190, v84
	v_add_f32_e32 v191, v191, v85
	v_add_f32_e32 v188, v188, v86
	v_add_f32_e32 v189, v189, v87
	v_add_f32_e32 v190, v190, v88
	v_add_f32_e32 v191, v191, v89
	v_add_f32_e32 v188, v188, v90
	v_add_f32_e32 v189, v189, v91
	v_add_f32_e32 v190, v190, v92
	v_add_f32_e32 v191, v191, v93
	v_add_f32_e32 v188, v188, v94
	v_add_f32_e32 v189, v189, v95
	v_add_f32_e32 v190, v190, v96
	v_add_f32_e32 v191, v191, v97
	v_cvt_pk_bf16_f32 v82, v82, v83
	v_cvt_pk_bf16_f32 v83, v84, v85
	v_cvt_pk_bf16_f32 v84, v86, v87
	v_cvt_pk_bf16_f32 v85, v88, v89
	v_cvt_pk_bf16_f32 v86, v90, v91
	v_cvt_pk_bf16_f32 v87, v92, v93
	v_cvt_pk_bf16_f32 v88, v94, v95
	v_cvt_pk_bf16_f32 v89, v96, v97
	v_add_f32_e32 v188, v188, v190
	v_add_f32_e32 v189, v189, v191
	s_waitcnt lgkmcnt(8)
	v_mfma_f32_32x32x16_bf16 v[50:65], v[166:169], v[82:85], v[50:65]
	v_mfma_f32_32x32x16_bf16 v[34:49], v[176:179], v[82:85], v[34:49]
	v_mfma_f32_32x32x16_bf16 v[18:33], v[180:183], v[82:85], v[18:33]
	v_mfma_f32_32x32x16_bf16 v[2:17], v[184:187], v[82:85], v[2:17]
	v_add_f32_e32 v0, v188, v189
	v_add_f32_e32 v159, v159, v0
	s_waitcnt lgkmcnt(0)
	v_mfma_f32_32x32x16_bf16 v[50:65], v[74:77], v[86:89], v[50:65]
	v_mfma_f32_32x32x16_bf16 v[34:49], v[78:81], v[86:89], v[34:49]
	v_mfma_f32_32x32x16_bf16 v[18:33], v[244:247], v[86:89], v[18:33]
	v_mfma_f32_32x32x16_bf16 v[2:17], v[248:251], v[86:89], v[2:17]
	s_branch .LBB0_931

; #define LAS __attribute__((address_space(3)))
; __device__ __forceinline__ float fexp2(float x) { return __builtin_amdgcn_exp2f(x); }
; __device__ __forceinline__ s16x4 vtr(const LAS unsigned char* p) { return __builtin_bit_cast(s16x4, __builtin_amdgcn_ds_read_tr16_b64_v4i16((LAS v4i16_t*)p)); }
; __device__ __forceinline__ bf16x8 cat8(s16x4 lo, s16x4 hi) { return (bf16x8){lo[0], lo[1], lo[2], lo[3], hi[0], hi[1], hi[2], hi[3]}; }
; template <int NEB>
; __device__ __forceinline__ void softmax_tile(f32x16& X0, f32x16& X1, float& m, float& l, f32x16 (&OT)[NEB]) {
;     ...
;     float s = 0.f;
; #pragma unroll
;     for (int r = 0; r < 16; ++r) { X0[r] = fexp2(X0[r] - m); X1[r] = fexp2(X1[r] - m); s += X0[r] + X1[r]; }
;     l += s;
; }
; template <int VRS, int NEB, bool SB = false>
; __device__ __forceinline__ void pv_tile(f32x16 (&OT)[NEB], const f32x16& X0, const f32x16& X1, const LAS unsigned char* vlane  ) {
; #pragma unroll
;     for (int kk = 0; kk < 4; ++kk) {
;         const bf16x8 pa = packp(kk < 2 ? X0 : X1, (kk & 1) * 8);
; #pragma unroll
;         for (int eb = 0; eb < NEB; ++eb) {
;             const s16x4 lo = vtr(vlane + (kk * 16) * VRS + eb * 64), hi = vtr(vlane + (kk * 16 + 8) * VRS + eb * 64);
;             OT[eb] = __builtin_amdgcn_mfma_f32_32x32x16_bf16(cat8(lo, hi), pa, OT[eb], 0, 0, 0);
;         }
;         if (SB) __builtin_amdgcn_sched_barrier(0);
;     }
; }
.Lpf1_nores:
	v_sub_f32_e32 v151, v163, v175
	v_sub_f32_e32 v66, v66, v151
	v_sub_f32_e32 v67, v67, v151
	v_sub_f32_e32 v68, v68, v151
	v_sub_f32_e32 v69, v69, v151
	v_sub_f32_e32 v70, v70, v151
	v_sub_f32_e32 v71, v71, v151
	v_sub_f32_e32 v72, v72, v151
	v_sub_f32_e32 v73, v73, v151
	v_sub_f32_e32 v74, v74, v151
	v_sub_f32_e32 v75, v75, v151
	v_sub_f32_e32 v76, v76, v151
	v_sub_f32_e32 v77, v77, v151
	v_sub_f32_e32 v78, v78, v151
	v_sub_f32_e32 v79, v79, v151
	v_sub_f32_e32 v80, v80, v151
	v_sub_f32_e32 v81, v81, v151
	v_exp_f32_e32 v66, v66
	v_exp_f32_e32 v67, v67
	v_exp_f32_e32 v68, v68
	v_exp_f32_e32 v69, v69
	v_exp_f32_e32 v70, v70
	v_exp_f32_e32 v71, v71
	v_exp_f32_e32 v72, v72
	v_exp_f32_e32 v73, v73
	v_exp_f32_e32 v74, v74
	v_exp_f32_e32 v75, v75
	v_exp_f32_e32 v76, v76
	v_exp_f32_e32 v77, v77
	v_exp_f32_e32 v78, v78
	v_exp_f32_e32 v79, v79
	v_exp_f32_e32 v80, v80
	v_exp_f32_e32 v81, v81
	v_add_f32_e32 v188, v66, v67
	v_add_f32_e32 v189, v68, v69
	v_add_f32_e32 v190, v70, v71
	v_add_f32_e32 v191, v72, v73
	v_add_f32_e32 v188, v188, v74
	v_add_f32_e32 v189, v189, v75
	v_add_f32_e32 v190, v190, v76
	v_add_f32_e32 v191, v191, v77
	v_add_f32_e32 v188, v188, v78
	v_add_f32_e32 v189, v189, v79
	v_add_f32_e32 v190, v190, v80
	v_add_f32_e32 v191, v191, v81
	v_cvt_pk_bf16_f32 v66, v66, v67
	v_cvt_pk_bf16_f32 v67, v68, v69
	v_cvt_pk_bf16_f32 v68, v70, v71
	v_cvt_pk_bf16_f32 v69, v72, v73
	v_cvt_pk_bf16_f32 v70, v74, v75
	v_cvt_pk_bf16_f32 v71, v76, v77
	v_cvt_pk_bf16_f32 v72, v78, v79
	v_cvt_pk_bf16_f32 v73, v80, v81
	ds_read_b64_tr_b16 v[74:75], v156 offset:62464
	ds_read_b64_tr_b16 v[76:77], v156 offset:65024
	ds_read_b64_tr_b16 v[78:79], v156 offset:62528
	ds_read_b64_tr_b16 v[80:81], v156 offset:65088
	ds_read_b64_tr_b16 v[244:245], v156 offset:62592
	ds_read_b64_tr_b16 v[246:247], v156 offset:65152
	ds_read_b64_tr_b16 v[248:249], v156 offset:62656
	ds_read_b64_tr_b16 v[250:251], v156 offset:65216
	s_waitcnt lgkmcnt(8)
	v_mfma_f32_32x32x16_bf16 v[50:65], v[166:169], v[66:69], v[50:65]
	v_mfma_f32_32x32x16_bf16 v[34:49], v[176:179], v[66:69], v[34:49]
	v_mfma_f32_32x32x16_bf16 v[18:33], v[180:183], v[66:69], v[18:33]
	v_mfma_f32_32x32x16_bf16 v[2:17], v[184:187], v[66:69], v[2:17]
	ds_read_b64_tr_b16 v[166:167], v157 offset:10240
	ds_read_b64_tr_b16 v[168:169], v157 offset:12800
	ds_read_b64_tr_b16 v[176:177], v157 offset:10304
	ds_read_b64_tr_b16 v[178:179], v157 offset:12864
	ds_read_b64_tr_b16 v[180:181], v157 offset:10368
	ds_read_b64_tr_b16 v[182:183], v157 offset:12928
	ds_read_b64_tr_b16 v[184:185], v157 offset:10432
	ds_read_b64_tr_b16 v[186:187], v157 offset:12992
	s_waitcnt lgkmcnt(8)
	v_mfma_f32_32x32x16_bf16 v[50:65], v[74:77], v[70:73], v[50:65]
	v_mfma_f32_32x32x16_bf16 v[34:49], v[78:81], v[70:73], v[34:49]
	v_mfma_f32_32x32x16_bf16 v[18:33], v[244:247], v[70:73], v[18:33]
	v_mfma_f32_32x32x16_bf16 v[2:17], v[248:251], v[70:73], v[2:17]
	ds_read_b64_tr_b16 v[74:75], v157 offset:15360
	ds_read_b64_tr_b16 v[76:77], v157 offset:17920
	ds_read_b64_tr_b16 v[78:79], v157 offset:15424
	ds_read_b64_tr_b16 v[80:81], v157 offset:17984
	ds_read_b64_tr_b16 v[244:245], v157 offset:15488
	ds_read_b64_tr_b16 v[246:247], v157 offset:18048
	ds_read_b64_tr_b16 v[248:249], v157 offset:15552
	ds_read_b64_tr_b16 v[250:251], v157 offset:18112
	v_sub_f32_e32 v82, v82, v151
	v_sub_f32_e32 v83, v83, v151
	v_sub_f32_e32 v84, v84, v151
	v_sub_f32_e32 v85, v85, v151
	v_sub_f32_e32 v86, v86, v151
	v_sub_f32_e32 v87, v87, v151
	v_sub_f32_e32 v88, v88, v151
	v_sub_f32_e32 v89, v89, v151
	v_sub_f32_e32 v90, v90, v151
	v_sub_f32_e32 v91, v91, v151
	v_sub_f32_e32 v92, v92, v151
	v_sub_f32_e32 v93, v93, v151
	v_sub_f32_e32 v94, v94, v151
	v_sub_f32_e32 v95, v95, v151
	v_sub_f32_e32 v96, v96, v151
	v_sub_f32_e32 v97, v97, v151
	v_exp_f32_e32 v82, v82
	v_exp_f32_e32 v83, v83
	v_exp_f32_e32 v84, v84
	v_exp_f32_e32 v85, v85
	v_exp_f32_e32 v86, v86
	v_exp_f32_e32 v87, v87
	v_exp_f32_e32 v88, v88
	v_exp_f32_e32 v89, v89
	v_exp_f32_e32 v90, v90
	v_exp_f32_e32 v91, v91
	v_exp_f32_e32 v92, v92
	v_exp_f32_e32 v93, v93
	v_exp_f32_e32 v94, v94
	v_exp_f32_e32 v95, v95
	v_exp_f32_e32 v96, v96
	v_exp_f32_e32 v97, v97
	v_add_f32_e32 v188, v188, v82
	v_add_f32_e32 v189, v189, v83
	v_add_f32_e32 v190, v190, v84
	v_add_f32_e32 v191, v191, v85
	v_add_f32_e32 v188, v188, v86
	v_add_f32_e32 v189, v189, v87
	v_add_f32_e32 v190, v190, v88
	v_add_f32_e32 v191, v191, v89
	v_add_f32_e32 v188, v188, v90
	v_add_f32_e32 v189, v189, v91
	v_add_f32_e32 v190, v190, v92
	v_add_f32_e32 v191, v191, v93
	v_add_f32_e32 v188, v188, v94
	v_add_f32_e32 v189, v189, v95
	v_add_f32_e32 v190, v190, v96
	v_add_f32_e32 v191, v191, v97
	v_cvt_pk_bf16_f32 v82, v82, v83
	v_cvt_pk_bf16_f32 v83, v84, v85
	v_cvt_pk_bf16_f32 v84, v86, v87
	v_cvt_pk_bf16_f32 v85, v88, v89
	v_cvt_pk_bf16_f32 v86, v90, v91
	v_cvt_pk_bf16_f32 v87, v92, v93
	v_cvt_pk_bf16_f32 v88, v94, v95
	v_cvt_pk_bf16_f32 v89, v96, v97
	v_add_f32_e32 v188, v188, v190
	v_add_f32_e32 v189, v189, v191
	s_waitcnt lgkmcnt(8)
	v_mfma_f32_32x32x16_bf16 v[50:65], v[166:169], v[82:85], v[50:65]
	v_mfma_f32_32x32x16_bf16 v[34:49], v[176:179], v[82:85], v[34:49]
	v_mfma_f32_32x32x16_bf16 v[18:33], v[180:183], v[82:85], v[18:33]
	v_mfma_f32_32x32x16_bf16 v[2:17], v[184:187], v[82:85], v[2:17]
	v_add_f32_e32 v0, v188, v189
	v_add_f32_e32 v159, v159, v0
	s_waitcnt lgkmcnt(0)
	v_mfma_f32_32x32x16_bf16 v[50:65], v[74:77], v[86:89], v[50:65]
	v_mfma_f32_32x32x16_bf16 v[34:49], v[78:81], v[86:89], v[34:49]
	v_mfma_f32_32x32x16_bf16 v[18:33], v[244:247], v[86:89], v[18:33]
	v_mfma_f32_32x32x16_bf16 v[2:17], v[248:251], v[86:89], v[2:17]
	s_branch .Lpf1_end
